# attention softmax row-max: 8 in-loop ds_bpermute cross-lane reductions replaced by v_permlane16/32_swap (same f32 max), on top of prio+weave
# speedup vs baseline: 1.0070x; 1.0041x over previous
; __device__ __forceinline__ void attn_unit(const WS& ws, int u, bool dry = false) {
;     ...
;     for (int nt = 0; nt < 2; ++nt) {
;       float mx = -INFINITY;
; #pragma unroll
;       for (int mt = 0; mt < 4; ++mt) mx = fmaxf(mx, fmaxf(fmaxf(s[mt][nt][0], s[mt][nt][1]), fmaxf(s[mt][nt][2], s[mt][nt][3])));
;       mx = fmaxf(mx, __shfl_xor(mx, 16)); mx = fmaxf(mx, __shfl_xor(mx, 32));
;       if (__builtin_amdgcn_ballot_w64(mx > mrun[nt]) != 0ull) {
;         const float mnew = fmaxf(mrun[nt], mx);
;         const float alpha = __builtin_amdgcn_exp2f(mrun[nt] - mnew);
;         mrun[nt] = mnew;
;         lsum[nt] *= alpha;
; #pragma unroll
;         for (int mt = 0; mt < 4; ++mt) oacc[mt][nt] = scale4(oacc[mt][nt], alpha);
;       }
.LBB0_865:
	s_nop 1
	v_max_f32_e32 v130, v117, v117
	v_max_f32_e32 v131, v116, v116
	v_max_f32_e32 v130, v131, v130
	v_max_f32_e32 v131, v121, v121
	v_max_f32_e32 v132, v120, v120
	v_max_f32_e32 v131, v132, v131
	v_max3_f32 v130, v114, v115, v130
	v_max3_f32 v131, v118, v119, v131
	v_max3_f32 v130, v130, s17, v131
	v_max_f32_e32 v131, v125, v125
	v_max_f32_e32 v132, v124, v124
	v_max_f32_e32 v131, v132, v131
	v_max_f32_e32 v132, v129, v129
	v_max_f32_e32 v133, v128, v128
	v_max_f32_e32 v132, v133, v132
	v_max3_f32 v131, v122, v123, v131
	v_max3_f32 v132, v126, v127, v132
	v_max3_f32 v130, v130, v131, v132
	v_mov_b32_e32 v131, v130
	s_nop 1
	v_permlane16_swap_b32_e32 v131, v130
	s_waitcnt lgkmcnt(0)
	v_max_f32_e32 v131, v131, v131
	v_max_f32_e32 v130, v130, v131
	v_mov_b32_e32 v131, v130
	s_nop 1
	v_permlane32_swap_b32_e32 v131, v130
	s_waitcnt lgkmcnt(0)
	v_max_f32_e32 v131, v131, v131
	v_max_f32_e32 v130, v130, v131
	v_cmp_gt_f32_e32 vcc, v130, v203
	s_cbranch_vccz .LBB0_867
	v_max_f32_e32 v130, v130, v130
	v_max_f32_e32 v131, v203, v203
	v_max_f32_e32 v130, v131, v130
	v_sub_f32_e32 v131, v203, v130
	v_exp_f32_e32 v131, v131
	v_mov_b32_e32 v203, v130
	v_mov_b32_e32 v132, v131
	v_mul_f32_e32 v201, v201, v131
	v_mul_f32_e32 v94, v94, v132
	v_mul_f32_e32 v95, v95, v132
	v_mul_f32_e32 v96, v96, v132
	v_mul_f32_e32 v97, v97, v132
	v_mov_b32_e32 v132, v131
	s_nop 0
	v_mul_f32_e32 v90, v90, v132
	v_mul_f32_e32 v91, v91, v132
	v_mul_f32_e32 v92, v92, v132
	v_mul_f32_e32 v93, v93, v132
	v_mov_b32_e32 v132, v131
	s_nop 0
	v_mul_f32_e32 v74, v74, v132
	v_mul_f32_e32 v75, v75, v132
	v_mul_f32_e32 v76, v76, v132
	v_mul_f32_e32 v77, v77, v132
	s_nop 0
	v_mul_f32_e32 v66, v66, v131
	v_mul_f32_e32 v67, v67, v131
	v_mul_f32_e32 v68, v68, v131
	v_mul_f32_e32 v69, v69, v131
.LBB0_867:
	v_max_f32_e32 v130, v101, v101
	v_max_f32_e32 v131, v100, v100
	v_max_f32_e32 v130, v131, v130
	v_max_f32_e32 v131, v105, v105
	v_max_f32_e32 v132, v104, v104
	v_max_f32_e32 v131, v132, v131
	v_max3_f32 v130, v98, v99, v130
	v_max3_f32 v131, v102, v103, v131
	v_max3_f32 v130, v130, s17, v131
	v_max_f32_e32 v131, v113, v113
	v_max_f32_e32 v132, v112, v112
	v_max_f32_e32 v131, v132, v131
	v_max_f32_e32 v132, v109, v109
	v_max_f32_e32 v133, v108, v108
	v_max_f32_e32 v132, v133, v132
	v_max3_f32 v131, v110, v111, v131
	v_max3_f32 v132, v106, v107, v132
	v_max3_f32 v130, v130, v131, v132
	v_mov_b32_e32 v131, v130
	s_nop 1
	v_permlane16_swap_b32_e32 v131, v130
	s_waitcnt lgkmcnt(0)
	v_max_f32_e32 v131, v131, v131
	v_max_f32_e32 v130, v130, v131
	v_mov_b32_e32 v131, v130
	s_nop 1
	v_permlane32_swap_b32_e32 v131, v130
	s_waitcnt lgkmcnt(0)
	v_max_f32_e32 v131, v131, v131
	v_max_f32_e32 v130, v130, v131
	v_cmp_gt_f32_e32 vcc, v130, v202
	s_cbranch_vccz .LBB0_869
	v_max_f32_e32 v130, v130, v130
	v_max_f32_e32 v131, v202, v202
	v_max_f32_e32 v130, v131, v130
	v_sub_f32_e32 v131, v202, v130
	v_exp_f32_e32 v131, v131
	v_mov_b32_e32 v202, v130
	v_mov_b32_e32 v132, v131
	v_mul_f32_e32 v176, v176, v131
	v_mul_f32_e32 v62, v62, v132
	v_mul_f32_e32 v63, v63, v132
	v_mul_f32_e32 v64, v64, v132
	v_mul_f32_e32 v65, v65, v132
	v_mov_b32_e32 v132, v131
	s_nop 0
	v_mul_f32_e32 v46, v46, v132
	v_mul_f32_e32 v47, v47, v132
	v_mul_f32_e32 v48, v48, v132
	v_mul_f32_e32 v49, v49, v132
	v_mov_b32_e32 v132, v131
	s_nop 0
	v_mul_f32_e32 v38, v38, v132
	v_mul_f32_e32 v39, v39, v132
	v_mul_f32_e32 v40, v40, v132
	v_mul_f32_e32 v41, v41, v132
	s_nop 0
	v_mul_f32_e32 v34, v34, v131
	v_mul_f32_e32 v35, v35, v131
	v_mul_f32_e32 v36, v36, v131
	v_mul_f32_e32 v37, v37, v131

; __device__ __forceinline__ void attn_unit(const WS& ws, int u, bool dry = false) {
;     ...
;     for (int nt = 0; nt < 2; ++nt) {
;       float mx = -INFINITY;
; #pragma unroll
;       for (int mt = 0; mt < 4; ++mt) mx = fmaxf(mx, fmaxf(fmaxf(s[mt][nt][0], s[mt][nt][1]), fmaxf(s[mt][nt][2], s[mt][nt][3])));
;       mx = fmaxf(mx, __shfl_xor(mx, 16)); mx = fmaxf(mx, __shfl_xor(mx, 32));
;       if (__builtin_amdgcn_ballot_w64(mx > mrun[nt]) != 0ull) {
;         const float mnew = fmaxf(mrun[nt], mx);
;         const float alpha = __builtin_amdgcn_exp2f(mrun[nt] - mnew);
;         mrun[nt] = mnew;
;         lsum[nt] *= alpha;
; #pragma unroll
;         for (int mt = 0; mt < 4; ++mt) oacc[mt][nt] = scale4(oacc[mt][nt], alpha);
;       }
;       const float mnew = mrun[nt];
;       float ps = 0.f;
; #pragma unroll
;       for (int mt = 0; mt < 4; ++mt)
; #pragma unroll
;         for (int jj = 0; jj < 4; ++jj) { const float pv = __builtin_amdgcn_exp2f(s[mt][nt][jj] - mnew); s[mt][nt][jj] = pv; ps += pv; }
;       lsum[nt] += ps;
.LBB0_871:
	v_max_f32_e32 v67, v129, v129
	v_max_f32_e32 v68, v128, v128
	v_max_f32_e32 v67, v68, v67
	v_max_f32_e32 v68, v125, v125
	v_max_f32_e32 v69, v124, v124
	v_max_f32_e32 v68, v69, v68
	v_max3_f32 v67, v126, v127, v67
	v_max3_f32 v68, v122, v123, v68
	v_max3_f32 v67, v67, s17, v68
	v_max_f32_e32 v68, v121, v121
	v_max_f32_e32 v69, v120, v120
	v_add_f32_e32 v66, 0, v227
	v_max_f32_e32 v68, v69, v68
	v_max_f32_e32 v69, v117, v117
	v_max_f32_e32 v74, v116, v116
	v_add_f32_e32 v66, v228, v66
	v_max_f32_e32 v69, v74, v69
	v_add_f32_e32 v66, v229, v66
	v_max3_f32 v68, v118, v119, v68
	v_max3_f32 v69, v114, v115, v69
	v_add_f32_e32 v66, v230, v66
	v_max3_f32 v67, v67, v68, v69
	v_add_f32_e32 v66, v231, v66
	v_mov_b32_e32 v68, v67
	s_nop 1
	v_permlane16_swap_b32_e32 v68, v67
	v_add_f32_e32 v66, v232, v66
	v_add_f32_e32 v66, v233, v66
	v_add_f32_e32 v66, v234, v66
	v_add_f32_e32 v66, v235, v66
	v_add_f32_e32 v66, v204, v66
	s_waitcnt lgkmcnt(0)
	v_max_f32_e32 v68, v68, v68
	v_add_f32_e32 v66, v221, v66
	v_max_f32_e32 v67, v67, v68
	v_add_f32_e32 v66, v223, v66
	v_mov_b32_e32 v68, v67
	s_nop 1
	v_permlane32_swap_b32_e32 v68, v67
	v_add_f32_e32 v66, v225, v66
	v_add_f32_e32 v66, v222, v66
	v_add_f32_e32 v66, v224, v66
	v_add_f32_e32 v66, v226, v66
	v_add_f32_e32 v221, v201, v66
	s_waitcnt lgkmcnt(0)
	v_max_f32_e32 v66, v68, v68
	v_max_f32_e32 v66, v67, v66
	v_cmp_gt_f32_e32 vcc, v66, v203
	s_cbranch_vccz .LBB0_879
	v_max_f32_e32 v66, v66, v66
	v_max_f32_e32 v67, v203, v203
	v_max_f32_e32 v204, v67, v66
	v_sub_f32_e32 v66, v203, v204
	v_exp_f32_e32 v69, v66
	s_nop 0
	v_mov_b32_e32 v66, v69
	v_mul_f32_e32 v201, v221, v69
	v_mul_f32_e32 v110, v130, v66
	v_mul_f32_e32 v111, v131, v66
	v_mul_f32_e32 v112, v132, v66
	v_mul_f32_e32 v113, v133, v66
	v_mov_b32_e32 v66, v69
	s_nop 0
	v_mul_f32_e32 v102, v134, v66
	v_mul_f32_e32 v103, v135, v66
	v_mul_f32_e32 v104, v136, v66
	v_mul_f32_e32 v105, v137, v66
	v_mov_b32_e32 v66, v69
	s_nop 0
	v_mul_f32_e32 v74, v138, v66
	v_mul_f32_e32 v75, v139, v66
	v_mul_f32_e32 v76, v140, v66
	v_mul_f32_e32 v77, v141, v66
	s_nop 0
	v_mul_f32_e32 v66, v142, v69
	v_mul_f32_e32 v67, v143, v69
	v_mul_f32_e32 v68, v144, v69
	v_mul_f32_e32 v69, v145, v69
	s_cbranch_execnz .LBB0_874

; __device__ __forceinline__ void attn_unit(const WS& ws, int u, bool dry = false) {
;     ...
;     for (int nt = 0; nt < 2; ++nt) {
;       float mx = -INFINITY;
; #pragma unroll
;       for (int mt = 0; mt < 4; ++mt) mx = fmaxf(mx, fmaxf(fmaxf(s[mt][nt][0], s[mt][nt][1]), fmaxf(s[mt][nt][2], s[mt][nt][3])));
;       mx = fmaxf(mx, __shfl_xor(mx, 16)); mx = fmaxf(mx, __shfl_xor(mx, 32));
;       if (__builtin_amdgcn_ballot_w64(mx > mrun[nt]) != 0ull) {
;         const float mnew = fmaxf(mrun[nt], mx);
;         const float alpha = __builtin_amdgcn_exp2f(mrun[nt] - mnew);
;         mrun[nt] = mnew;
;         lsum[nt] *= alpha;
; #pragma unroll
;         for (int mt = 0; mt < 4; ++mt) oacc[mt][nt] = scale4(oacc[mt][nt], alpha);
;       }
;       const float mnew = mrun[nt];
;       float ps = 0.f;
; #pragma unroll
;       for (int mt = 0; mt < 4; ++mt)
; #pragma unroll
;         for (int jj = 0; jj < 4; ++jj) { const float pv = __builtin_amdgcn_exp2f(s[mt][nt][jj] - mnew); s[mt][nt][jj] = pv; ps += pv; }
;       lsum[nt] += ps;
.LBB0_874:
	v_max_f32_e32 v131, v37, v37
	v_max_f32_e32 v132, v36, v36
	v_max_f32_e32 v131, v132, v131
	v_max_f32_e32 v132, v41, v41
	v_max_f32_e32 v133, v40, v40
	v_max_f32_e32 v132, v133, v132
	v_max3_f32 v131, v34, v35, v131
	v_max3_f32 v132, v38, v39, v132
	v_max3_f32 v131, v131, s17, v132
	v_max_f32_e32 v132, v49, v49
	v_max_f32_e32 v133, v48, v48
	v_add_f32_e32 v130, 0, v208
	v_max_f32_e32 v132, v133, v132
	v_max_f32_e32 v133, v65, v65
	v_max_f32_e32 v134, v64, v64
	v_add_f32_e32 v130, v209, v130
	v_max_f32_e32 v133, v134, v133
	v_add_f32_e32 v130, v210, v130
	v_max3_f32 v132, v46, v47, v132
	v_max3_f32 v133, v62, v63, v133
	v_add_f32_e32 v130, v211, v130
	v_max3_f32 v131, v131, v132, v133
	v_add_f32_e32 v130, v212, v130
	v_mov_b32_e32 v132, v131
	s_nop 1
	v_permlane16_swap_b32_e32 v132, v131
	v_add_f32_e32 v130, v213, v130
	v_add_f32_e32 v130, v214, v130
	v_add_f32_e32 v130, v215, v130
	v_add_f32_e32 v130, v216, v130
	v_add_f32_e32 v130, v205, v130
	s_waitcnt lgkmcnt(0)
	v_max_f32_e32 v132, v132, v132
	v_add_f32_e32 v130, v206, v130
	v_max_f32_e32 v131, v131, v132
	v_add_f32_e32 v130, v207, v130
	v_mov_b32_e32 v132, v131
	s_nop 1
	v_permlane32_swap_b32_e32 v132, v131
	v_add_f32_e32 v130, v219, v130
	v_add_f32_e32 v130, v217, v130
	v_add_f32_e32 v130, v218, v130
	v_add_f32_e32 v130, v220, v130
	v_add_f32_e32 v205, v176, v130
	s_waitcnt lgkmcnt(0)
	v_max_f32_e32 v130, v132, v132
	v_max_f32_e32 v130, v131, v130
	v_cmp_gt_f32_e32 vcc, v130, v202
	s_cbranch_vccz .LBB0_880
	v_max_f32_e32 v130, v130, v130
	v_max_f32_e32 v131, v202, v202
	v_max_f32_e32 v203, v131, v130
	v_sub_f32_e32 v130, v202, v203
	v_exp_f32_e32 v133, v130
	s_nop 0
	v_mov_b32_e32 v130, v133
	v_mul_f32_e32 v176, v205, v133
	v_mul_f32_e32 v142, v94, v130
	v_mul_f32_e32 v143, v95, v130
	v_mul_f32_e32 v144, v96, v130
	v_mul_f32_e32 v145, v97, v130
	v_mov_b32_e32 v130, v133
	s_nop 0
	v_mul_f32_e32 v138, v90, v130
	v_mul_f32_e32 v139, v91, v130
	v_mul_f32_e32 v140, v92, v130
	v_mul_f32_e32 v141, v93, v130
	v_mov_b32_e32 v130, v133
	s_nop 0
	v_mul_f32_e32 v134, v98, v130
	v_mul_f32_e32 v135, v99, v130
	v_mul_f32_e32 v136, v100, v130
	v_mul_f32_e32 v137, v101, v130
	s_nop 0
	v_mul_f32_e32 v130, v106, v133
	v_mul_f32_e32 v131, v107, v133
	v_mul_f32_e32 v132, v108, v133
	v_mul_f32_e32 v133, v109, v133
	s_cbranch_execnz .LBB0_877
